# combination: G1 partial loads at tile head + K_Q one-load-per-row + w_out wait cleanup + GEMM DMA-first, on top of the G1 one-load-per-row epilogue
# baseline (speedup 1.0000x reference)
; #define PG8_STAGE(bufoff, gbase, voff) do { _Pragma("unroll") for (int _i = 0; _i < 2; ++_i) \
;         __builtin_amdgcn_global_load_lds((const unsigned*)((const char*)(gbase) + (voff)[_i]), (LAS unsigned*)(lds + (bufoff) + ldsw + _i * 8192), 16, 0, 0); } while (0)
; #define PG8_LDA(dst, b, h) do { _Pragma("unroll") for (int m = 0; m < 4; ++m) _Pragma("unroll") for (int k = 0; k < 2; ++k) dst[m][k] = *(const LAS bf16x8*)(lds + PG8_SA(b, h) + aoff + m * 2048 + k * 1024); } while (0)
; #define PG8_LDB(dst, b, h) do { _Pragma("unroll") for (int n = 0; n < 2; ++n) _Pragma("unroll") for (int k = 0; k < 2; ++k) dst[n][k] = *(const LAS bf16x8*)(lds + PG8_SB(b, h) + boff + n * 2048 + k * 1024); } while (0)
; #define PG8_MMA(ai, bj, At, Bt) do { __builtin_amdgcn_s_setprio(1); _Pragma("unroll") for (int m = 0; m < 4; ++m) _Pragma("unroll") for (int n = 0; n < 2; ++n) _Pragma("unroll") for (int k = 0; k < 2; ++k) \
;         acc[ai][bj][m][n] = __builtin_amdgcn_mfma_f32_16x16x32_bf16(Bt[n][k], At[m][k], acc[ai][bj][m][n], 0, 0, 0); __builtin_amdgcn_s_setprio(0); } while (0)
; #define PG8_WAIT_V(n) asm volatile("s_waitcnt vmcnt(" #n ")" ::: "memory")
; #define PG8_WAIT_L(n) asm volatile("s_waitcnt lgkmcnt(" #n ")" ::: "memory")
; #define PG8_BAR __builtin_amdgcn_s_barrier()
; #define PG8_SCHED __builtin_amdgcn_sched_barrier(0)
; template <class EpiT>
; __device__ __forceinline__ void gemm_phase(LAS unsigned char* lds, const Gemm g, const StaticOrder& S, const EpiT& E, int wv) {
;     ...
;             PG8_LDB(B0, 0, 0); PG8_LDB(B1, 0, 1); PG8_SCHED; PG8_LDA(At, 0, 0); PG8_STAGE(PG8_SA(1, 1), a1 + hA, voffA);
;             PG8_WAIT_V(8); PG8_WAIT_L(0); PG8_BAR; PG8_MMA(0, 0, At, B0); PG8_MMA(0, 1, At, B1); PG8_BAR; PG8_SCHED;
;             PG8_LDA(At, 0, 1); PG8_STAGE(PG8_SB(0, 0), b2, voffB); PG8_STAGE(PG8_SB(0, 1), b2 + hB, voffB); PG8_STAGE(PG8_SA(0, 0), a2, voffA);
;             PG8_WAIT_V(8); PG8_WAIT_L(0); PG8_BAR; PG8_MMA(1, 0, At, B0); PG8_MMA(1, 1, At, B1); PG8_BAR; PG8_SCHED;
.Lg1rd_skipA:
.LBB0_271:
	s_add_i32 s42, s22, 2
	s_add_u32 s43, s0, 0x80
	s_addc_u32 s23, s1, 0
	s_add_i32 s64, 0, 0x10000
	s_cmp_eq_u32 s52, s22
	s_cselect_b32 s23, s19, s23
	s_cselect_b32 s22, s18, s43
	s_cselect_b32 s45, s21, s41
	s_cselect_b32 s44, s20, s40
	s_add_i32 s43, 0, 0x14000
	s_add_i32 m0, s14, 0xc000
	s_nop 0
	global_load_lds_dwordx4 v196, s[0:1]
	s_add_i32 m0, s14, 0xe000
	s_nop 0
	global_load_lds_dwordx4 v198, s[0:1]
	v_add_u32_e32 v0, s64, v234
	ds_read_b128 v[134:137], v0
	ds_read_b128 v[138:141], v0 offset:1024
	ds_read_b128 v[142:145], v0 offset:2048
	ds_read_b128 v[146:149], v0 offset:3072
	v_add_u32_e32 v0, s43, v234
	ds_read_b128 v[150:153], v0
	ds_read_b128 v[154:157], v0 offset:1024
	ds_read_b128 v[158:161], v0 offset:2048
	ds_read_b128 v[162:165], v0 offset:3072
	ds_read_b128 v[166:169], v242
	ds_read_b128 v[170:173], v242 offset:1024
	ds_read_b128 v[174:177], v242 offset:2048
	ds_read_b128 v[178:181], v242 offset:3072
	ds_read_b128 v[204:207], v242 offset:4096
	ds_read_b128 v[208:211], v242 offset:5120
	ds_read_b128 v[212:215], v242 offset:6144
	ds_read_b128 v[216:219], v242 offset:7168
	s_waitcnt vmcnt(8)
	s_waitcnt lgkmcnt(0)
	s_barrier
	s_setprio 1
	s_waitcnt lgkmcnt(0)
	v_mfma_f32_16x16x32_bf16 v[130:133], v[134:137], v[166:169], v[130:133]
	v_mfma_f32_16x16x32_bf16 v[126:129], v[142:145], v[166:169], v[126:129]
	v_mfma_f32_16x16x32_bf16 v[114:117], v[134:137], v[174:177], v[114:117]
	v_mfma_f32_16x16x32_bf16 v[110:113], v[142:145], v[174:177], v[110:113]
	v_mfma_f32_16x16x32_bf16 v[98:101], v[134:137], v[204:207], v[98:101]
	v_mfma_f32_16x16x32_bf16 v[94:97], v[142:145], v[204:207], v[94:97]
	v_mfma_f32_16x16x32_bf16 v[82:85], v[134:137], v[212:215], v[82:85]
	v_mfma_f32_16x16x32_bf16 v[78:81], v[142:145], v[212:215], v[78:81]
	v_mfma_f32_16x16x32_bf16 v[130:133], v[138:141], v[170:173], v[130:133]
	v_mfma_f32_16x16x32_bf16 v[126:129], v[146:149], v[170:173], v[126:129]
	v_mfma_f32_16x16x32_bf16 v[114:117], v[138:141], v[178:181], v[114:117]
	v_mfma_f32_16x16x32_bf16 v[110:113], v[146:149], v[178:181], v[110:113]
	v_mfma_f32_16x16x32_bf16 v[98:101], v[138:141], v[208:211], v[98:101]
	v_mfma_f32_16x16x32_bf16 v[94:97], v[146:149], v[208:211], v[94:97]
	v_mfma_f32_16x16x32_bf16 v[82:85], v[138:141], v[216:219], v[82:85]
	v_mfma_f32_16x16x32_bf16 v[78:81], v[146:149], v[216:219], v[78:81]
	s_setprio 0
	s_setprio 1
	v_mfma_f32_16x16x32_bf16 v[122:125], v[150:153], v[166:169], v[122:125]
	v_mfma_f32_16x16x32_bf16 v[118:121], v[158:161], v[166:169], v[118:121]
	v_mfma_f32_16x16x32_bf16 v[106:109], v[150:153], v[174:177], v[106:109]
	v_mfma_f32_16x16x32_bf16 v[102:105], v[158:161], v[174:177], v[102:105]
	v_mfma_f32_16x16x32_bf16 v[90:93], v[150:153], v[204:207], v[90:93]
	v_mfma_f32_16x16x32_bf16 v[86:89], v[158:161], v[204:207], v[86:89]
	v_mfma_f32_16x16x32_bf16 v[74:77], v[150:153], v[212:215], v[74:77]
	v_mfma_f32_16x16x32_bf16 v[70:73], v[158:161], v[212:215], v[70:73]
	v_mfma_f32_16x16x32_bf16 v[122:125], v[154:157], v[170:173], v[122:125]
	v_mfma_f32_16x16x32_bf16 v[118:121], v[162:165], v[170:173], v[118:121]
	v_mfma_f32_16x16x32_bf16 v[106:109], v[154:157], v[178:181], v[106:109]
	v_mfma_f32_16x16x32_bf16 v[102:105], v[162:165], v[178:181], v[102:105]
	v_mfma_f32_16x16x32_bf16 v[90:93], v[154:157], v[208:211], v[90:93]
	v_mfma_f32_16x16x32_bf16 v[86:89], v[162:165], v[208:211], v[86:89]
	v_mfma_f32_16x16x32_bf16 v[74:77], v[154:157], v[216:219], v[74:77]
	v_mfma_f32_16x16x32_bf16 v[70:73], v[162:165], v[216:219], v[70:73]
	s_setprio 0
	s_barrier
	s_add_i32 s64, s64, s13
	s_mov_b32 m0, s64
	s_add_u32 s36, s44, 0x80
	s_addc_u32 s37, s45, 0
	global_load_lds_dwordx4 v182, s[44:45]
	s_add_i32 m0, s64, 0x2000
	s_add_i32 s43, s43, s13
	global_load_lds_dwordx4 v186, s[44:45]
	s_add_u32 s44, s44, s8
	s_addc_u32 s45, s45, 0
	s_mov_b32 m0, s43
	s_add_u32 s38, s44, 0x80
	s_addc_u32 s39, s45, 0
	global_load_lds_dwordx4 v182, s[44:45]
	s_add_i32 m0, s43, 0x2000
	s_add_u32 s46, s22, 0x80
	s_addc_u32 s47, s23, 0
	global_load_lds_dwordx4 v186, s[44:45]
	s_mov_b32 m0, s14
	s_nop 0
	global_load_lds_dwordx4 v14, s[22:23]
	s_mov_b32 m0, s15
	s_nop 0
	global_load_lds_dwordx4 v184, s[22:23]
	ds_read_b128 v[166:169], v242 offset:16384
	ds_read_b128 v[170:173], v242 offset:17408
	ds_read_b128 v[174:177], v242 offset:18432
	ds_read_b128 v[178:181], v242 offset:19456
	ds_read_b128 v[204:207], v242 offset:20480
	ds_read_b128 v[208:211], v242 offset:21504
	ds_read_b128 v[212:215], v242 offset:22528
	ds_read_b128 v[216:219], v242 offset:23552
	s_waitcnt vmcnt(8)
	s_waitcnt lgkmcnt(0)
	s_barrier
; #define PG8_STAGE(bufoff, gbase, voff) do { _Pragma("unroll") for (int _i = 0; _i < 2; ++_i) \
;         __builtin_amdgcn_global_load_lds((const unsigned*)((const char*)(gbase) + (voff)[_i]), (LAS unsigned*)(lds + (bufoff) + ldsw + _i * 8192), 16, 0, 0); } while (0)
; #define PG8_LDA(dst, b, h) do { _Pragma("unroll") for (int m = 0; m < 4; ++m) _Pragma("unroll") for (int k = 0; k < 2; ++k) dst[m][k] = *(const LAS bf16x8*)(lds + PG8_SA(b, h) + aoff + m * 2048 + k * 1024); } while (0)
; #define PG8_LDB(dst, b, h) do { _Pragma("unroll") for (int n = 0; n < 2; ++n) _Pragma("unroll") for (int k = 0; k < 2; ++k) dst[n][k] = *(const LAS bf16x8*)(lds + PG8_SB(b, h) + boff + n * 2048 + k * 1024); } while (0)
; #define PG8_MMA(ai, bj, At, Bt) do { __builtin_amdgcn_s_setprio(1); _Pragma("unroll") for (int m = 0; m < 4; ++m) _Pragma("unroll") for (int n = 0; n < 2; ++n) _Pragma("unroll") for (int k = 0; k < 2; ++k) \
;         acc[ai][bj][m][n] = __builtin_amdgcn_mfma_f32_16x16x32_bf16(Bt[n][k], At[m][k], acc[ai][bj][m][n], 0, 0, 0); __builtin_amdgcn_s_setprio(0); } while (0)
; #define PG8_WAIT_V(n) asm volatile("s_waitcnt vmcnt(" #n ")" ::: "memory")
; #define PG8_WAIT_L(n) asm volatile("s_waitcnt lgkmcnt(" #n ")" ::: "memory")
; #define PG8_BAR __builtin_amdgcn_s_barrier()
; #define PG8_SCHED __builtin_amdgcn_sched_barrier(0)
; template <class EpiT>
; __device__ __forceinline__ void gemm_phase(LAS unsigned char* lds, const Gemm g, const StaticOrder& S, const EpiT& E, int wv) {
;     ...
;             PG8_WAIT_V(8); PG8_WAIT_L(0); PG8_BAR; PG8_MMA(1, 0, At, B0); PG8_MMA(1, 1, At, B1); PG8_BAR; PG8_SCHED;
;             PG8_LDB(B0, 1, 0); PG8_LDB(B1, 1, 1); PG8_SCHED; PG8_LDA(At, 1, 0); PG8_STAGE(PG8_SA(0, 1), a2 + hA, voffA);
;             PG8_WAIT_V(8); PG8_WAIT_L(0); PG8_BAR; PG8_MMA(0, 0, At, B0); PG8_MMA(0, 1, At, B1); PG8_BAR; PG8_SCHED;
	s_setprio 1
	s_waitcnt lgkmcnt(0)
	v_mfma_f32_16x16x32_bf16 v[66:69], v[134:137], v[166:169], v[66:69]
	v_mfma_f32_16x16x32_bf16 v[62:65], v[142:145], v[166:169], v[62:65]
	v_mfma_f32_16x16x32_bf16 v[50:53], v[134:137], v[174:177], v[50:53]
	v_mfma_f32_16x16x32_bf16 v[46:49], v[142:145], v[174:177], v[46:49]
	v_mfma_f32_16x16x32_bf16 v[34:37], v[134:137], v[204:207], v[34:37]
	v_mfma_f32_16x16x32_bf16 v[30:33], v[142:145], v[204:207], v[30:33]
	v_mfma_f32_16x16x32_bf16 v[18:21], v[134:137], v[212:215], v[18:21]
	v_mfma_f32_16x16x32_bf16 v[10:13], v[142:145], v[212:215], v[10:13]
	v_mfma_f32_16x16x32_bf16 v[66:69], v[138:141], v[170:173], v[66:69]
	v_mfma_f32_16x16x32_bf16 v[62:65], v[146:149], v[170:173], v[62:65]
	v_mfma_f32_16x16x32_bf16 v[50:53], v[138:141], v[178:181], v[50:53]
	v_mfma_f32_16x16x32_bf16 v[46:49], v[146:149], v[178:181], v[46:49]
	v_mfma_f32_16x16x32_bf16 v[34:37], v[138:141], v[208:211], v[34:37]
	v_mfma_f32_16x16x32_bf16 v[30:33], v[146:149], v[208:211], v[30:33]
	v_mfma_f32_16x16x32_bf16 v[18:21], v[138:141], v[216:219], v[18:21]
	v_mfma_f32_16x16x32_bf16 v[10:13], v[146:149], v[216:219], v[10:13]
	s_setprio 0
	s_setprio 1
	v_mfma_f32_16x16x32_bf16 v[58:61], v[150:153], v[166:169], v[58:61]
	v_mfma_f32_16x16x32_bf16 v[54:57], v[158:161], v[166:169], v[54:57]
	v_mfma_f32_16x16x32_bf16 v[42:45], v[150:153], v[174:177], v[42:45]
	v_mfma_f32_16x16x32_bf16 v[38:41], v[158:161], v[174:177], v[38:41]
	v_mfma_f32_16x16x32_bf16 v[26:29], v[150:153], v[204:207], v[26:29]
	v_mfma_f32_16x16x32_bf16 v[22:25], v[158:161], v[204:207], v[22:25]
	v_mfma_f32_16x16x32_bf16 v[6:9], v[150:153], v[212:215], v[6:9]
	v_mfma_f32_16x16x32_bf16 v[2:5], v[158:161], v[212:215], v[2:5]
	v_mfma_f32_16x16x32_bf16 v[58:61], v[154:157], v[170:173], v[58:61]
	v_mfma_f32_16x16x32_bf16 v[54:57], v[162:165], v[170:173], v[54:57]
	v_mfma_f32_16x16x32_bf16 v[42:45], v[154:157], v[178:181], v[42:45]
	v_mfma_f32_16x16x32_bf16 v[38:41], v[162:165], v[178:181], v[38:41]
	v_mfma_f32_16x16x32_bf16 v[26:29], v[154:157], v[208:211], v[26:29]
	v_mfma_f32_16x16x32_bf16 v[22:25], v[162:165], v[208:211], v[22:25]
	v_mfma_f32_16x16x32_bf16 v[6:9], v[154:157], v[216:219], v[6:9]
	v_mfma_f32_16x16x32_bf16 v[2:5], v[162:165], v[216:219], v[2:5]
	s_setprio 0
	s_barrier
	s_add_i32 s43, 0, 0x18000
	s_add_i32 s44, 0, 0x1c000
	s_add_u32 s22, s22, s4
	s_addc_u32 s23, s23, 0
	s_mov_b32 m0, s88
	s_nop 0
	global_load_lds_dwordx4 v14, s[22:23]
	s_mov_b32 m0, s89
	s_nop 0
	global_load_lds_dwordx4 v184, s[22:23]
	v_add_u32_e32 v0, s43, v234
	ds_read_b128 v[134:137], v0
	ds_read_b128 v[138:141], v0 offset:1024
	ds_read_b128 v[142:145], v0 offset:2048
	ds_read_b128 v[146:149], v0 offset:3072
	v_add_u32_e32 v0, s44, v234
	ds_read_b128 v[150:153], v0
	ds_read_b128 v[154:157], v0 offset:1024
	ds_read_b128 v[158:161], v0 offset:2048
	ds_read_b128 v[162:165], v0 offset:3072
	ds_read_b128 v[166:169], v242 offset:32768
	ds_read_b128 v[170:173], v242 offset:33792
	ds_read_b128 v[174:177], v242 offset:34816
	ds_read_b128 v[178:181], v242 offset:35840
	ds_read_b128 v[204:207], v242 offset:36864
	ds_read_b128 v[208:211], v242 offset:37888
	ds_read_b128 v[212:215], v242 offset:38912
	ds_read_b128 v[216:219], v242 offset:39936
	s_waitcnt vmcnt(8)
	s_waitcnt lgkmcnt(0)
	s_barrier
	s_setprio 1
	s_waitcnt lgkmcnt(0)
	v_mfma_f32_16x16x32_bf16 v[130:133], v[134:137], v[166:169], v[130:133]
	v_mfma_f32_16x16x32_bf16 v[126:129], v[142:145], v[166:169], v[126:129]
	v_mfma_f32_16x16x32_bf16 v[114:117], v[134:137], v[174:177], v[114:117]
	v_mfma_f32_16x16x32_bf16 v[110:113], v[142:145], v[174:177], v[110:113]
	v_mfma_f32_16x16x32_bf16 v[98:101], v[134:137], v[204:207], v[98:101]
	v_mfma_f32_16x16x32_bf16 v[94:97], v[142:145], v[204:207], v[94:97]
	v_mfma_f32_16x16x32_bf16 v[82:85], v[134:137], v[212:215], v[82:85]
	v_mfma_f32_16x16x32_bf16 v[78:81], v[142:145], v[212:215], v[78:81]
	v_mfma_f32_16x16x32_bf16 v[130:133], v[138:141], v[170:173], v[130:133]
	v_mfma_f32_16x16x32_bf16 v[126:129], v[146:149], v[170:173], v[126:129]
	v_mfma_f32_16x16x32_bf16 v[114:117], v[138:141], v[178:181], v[114:117]
	v_mfma_f32_16x16x32_bf16 v[110:113], v[146:149], v[178:181], v[110:113]
	v_mfma_f32_16x16x32_bf16 v[98:101], v[138:141], v[208:211], v[98:101]
	v_mfma_f32_16x16x32_bf16 v[94:97], v[146:149], v[208:211], v[94:97]
	v_mfma_f32_16x16x32_bf16 v[82:85], v[138:141], v[216:219], v[82:85]
	v_mfma_f32_16x16x32_bf16 v[78:81], v[146:149], v[216:219], v[78:81]
	s_setprio 0
	s_setprio 1
	v_mfma_f32_16x16x32_bf16 v[122:125], v[150:153], v[166:169], v[122:125]
	v_mfma_f32_16x16x32_bf16 v[118:121], v[158:161], v[166:169], v[118:121]
	v_mfma_f32_16x16x32_bf16 v[106:109], v[150:153], v[174:177], v[106:109]
	v_mfma_f32_16x16x32_bf16 v[102:105], v[158:161], v[174:177], v[102:105]
	v_mfma_f32_16x16x32_bf16 v[90:93], v[150:153], v[204:207], v[90:93]
	v_mfma_f32_16x16x32_bf16 v[86:89], v[158:161], v[204:207], v[86:89]
	v_mfma_f32_16x16x32_bf16 v[74:77], v[150:153], v[212:215], v[74:77]
	v_mfma_f32_16x16x32_bf16 v[70:73], v[158:161], v[212:215], v[70:73]
	v_mfma_f32_16x16x32_bf16 v[122:125], v[154:157], v[170:173], v[122:125]
	v_mfma_f32_16x16x32_bf16 v[118:121], v[162:165], v[170:173], v[118:121]
	v_mfma_f32_16x16x32_bf16 v[106:109], v[154:157], v[178:181], v[106:109]
	v_mfma_f32_16x16x32_bf16 v[102:105], v[162:165], v[178:181], v[102:105]
	v_mfma_f32_16x16x32_bf16 v[90:93], v[154:157], v[208:211], v[90:93]
	v_mfma_f32_16x16x32_bf16 v[86:89], v[162:165], v[208:211], v[86:89]
	v_mfma_f32_16x16x32_bf16 v[74:77], v[154:157], v[216:219], v[74:77]
	v_mfma_f32_16x16x32_bf16 v[70:73], v[162:165], v[216:219], v[70:73]
	s_setprio 0
	s_barrier
; #define PG8_STAGE(bufoff, gbase, voff) do { _Pragma("unroll") for (int _i = 0; _i < 2; ++_i) \
;         __builtin_amdgcn_global_load_lds((const unsigned*)((const char*)(gbase) + (voff)[_i]), (LAS unsigned*)(lds + (bufoff) + ldsw + _i * 8192), 16, 0, 0); } while (0)
; #define PG8_LDA(dst, b, h) do { _Pragma("unroll") for (int m = 0; m < 4; ++m) _Pragma("unroll") for (int k = 0; k < 2; ++k) dst[m][k] = *(const LAS bf16x8*)(lds + PG8_SA(b, h) + aoff + m * 2048 + k * 1024); } while (0)
; #define PG8_MMA(ai, bj, At, Bt) do { __builtin_amdgcn_s_setprio(1); _Pragma("unroll") for (int m = 0; m < 4; ++m) _Pragma("unroll") for (int n = 0; n < 2; ++n) _Pragma("unroll") for (int k = 0; k < 2; ++k) \
;         acc[ai][bj][m][n] = __builtin_amdgcn_mfma_f32_16x16x32_bf16(Bt[n][k], At[m][k], acc[ai][bj][m][n], 0, 0, 0); __builtin_amdgcn_s_setprio(0); } while (0)
; #define PG8_WAIT_V(n) asm volatile("s_waitcnt vmcnt(" #n ")" ::: "memory")
; #define PG8_WAIT_L(n) asm volatile("s_waitcnt lgkmcnt(" #n ")" ::: "memory")
; #define PG8_BAR __builtin_amdgcn_s_barrier()
; #define PG8_SCHED __builtin_amdgcn_sched_barrier(0)
; template <class EpiT>
; __device__ __forceinline__ void gemm_phase(LAS unsigned char* lds, const Gemm g, const StaticOrder& S, const EpiT& E, int wv) {
;     ...
;             PG8_LDA(At, 1, 1); PG8_STAGE(PG8_SB(1, 0), b3, voffB); PG8_STAGE(PG8_SB(1, 1), b3 + hB, voffB); PG8_STAGE(PG8_SA(1, 0), a3, voffA);
;             PG8_WAIT_V(8); PG8_WAIT_L(0); PG8_BAR; PG8_MMA(1, 0, At, B0); PG8_MMA(1, 1, At, B1); PG8_BAR; PG8_SCHED;
;         }
	s_add_i32 s22, s43, s13
	s_mov_b32 m0, s22
	s_nop 0
	global_load_lds_dwordx4 v182, s[36:37]
	s_add_i32 m0, s22, 0x2000
	s_add_i32 s22, s44, s13
	global_load_lds_dwordx4 v186, s[36:37]
	s_mov_b32 m0, s22
	s_nop 0
	global_load_lds_dwordx4 v182, s[38:39]
	s_add_i32 m0, s22, 0x2000
	s_nop 0
	global_load_lds_dwordx4 v186, s[38:39]
	s_mov_b32 m0, s72
	s_nop 0
	global_load_lds_dwordx4 v14, s[46:47]
	s_mov_b32 m0, s73
	s_nop 0
	global_load_lds_dwordx4 v184, s[46:47]
	ds_read_b128 v[166:169], v242 offset:49152
	ds_read_b128 v[170:173], v242 offset:50176
	ds_read_b128 v[174:177], v242 offset:51200
	ds_read_b128 v[178:181], v242 offset:52224
	ds_read_b128 v[204:207], v242 offset:53248
	ds_read_b128 v[208:211], v242 offset:54272
	ds_read_b128 v[212:215], v242 offset:55296
	ds_read_b128 v[216:219], v242 offset:56320
	s_waitcnt vmcnt(8)
	s_waitcnt lgkmcnt(0)
	s_barrier
	s_setprio 1
	s_waitcnt lgkmcnt(0)
	v_mfma_f32_16x16x32_bf16 v[66:69], v[134:137], v[166:169], v[66:69]
	v_mfma_f32_16x16x32_bf16 v[62:65], v[142:145], v[166:169], v[62:65]
	v_mfma_f32_16x16x32_bf16 v[50:53], v[134:137], v[174:177], v[50:53]
	v_mfma_f32_16x16x32_bf16 v[46:49], v[142:145], v[174:177], v[46:49]
	v_mfma_f32_16x16x32_bf16 v[34:37], v[134:137], v[204:207], v[34:37]
	v_mfma_f32_16x16x32_bf16 v[30:33], v[142:145], v[204:207], v[30:33]
	v_mfma_f32_16x16x32_bf16 v[18:21], v[134:137], v[212:215], v[18:21]
	v_mfma_f32_16x16x32_bf16 v[10:13], v[142:145], v[212:215], v[10:13]
	v_mfma_f32_16x16x32_bf16 v[66:69], v[138:141], v[170:173], v[66:69]
	v_mfma_f32_16x16x32_bf16 v[62:65], v[146:149], v[170:173], v[62:65]
	v_mfma_f32_16x16x32_bf16 v[50:53], v[138:141], v[178:181], v[50:53]
	v_mfma_f32_16x16x32_bf16 v[46:49], v[146:149], v[178:181], v[46:49]
	v_mfma_f32_16x16x32_bf16 v[34:37], v[138:141], v[208:211], v[34:37]
	v_mfma_f32_16x16x32_bf16 v[30:33], v[146:149], v[208:211], v[30:33]
	v_mfma_f32_16x16x32_bf16 v[18:21], v[138:141], v[216:219], v[18:21]
	v_mfma_f32_16x16x32_bf16 v[10:13], v[146:149], v[216:219], v[10:13]
	s_setprio 0
	s_setprio 1
	v_mfma_f32_16x16x32_bf16 v[58:61], v[150:153], v[166:169], v[58:61]
	v_mfma_f32_16x16x32_bf16 v[54:57], v[158:161], v[166:169], v[54:57]
	v_mfma_f32_16x16x32_bf16 v[42:45], v[150:153], v[174:177], v[42:45]
	v_mfma_f32_16x16x32_bf16 v[38:41], v[158:161], v[174:177], v[38:41]
	v_mfma_f32_16x16x32_bf16 v[26:29], v[150:153], v[204:207], v[26:29]
	v_mfma_f32_16x16x32_bf16 v[22:25], v[158:161], v[204:207], v[22:25]
	v_mfma_f32_16x16x32_bf16 v[6:9], v[150:153], v[212:215], v[6:9]
	v_mfma_f32_16x16x32_bf16 v[2:5], v[158:161], v[212:215], v[2:5]
	v_mfma_f32_16x16x32_bf16 v[58:61], v[154:157], v[170:173], v[58:61]
	v_mfma_f32_16x16x32_bf16 v[54:57], v[162:165], v[170:173], v[54:57]
	v_mfma_f32_16x16x32_bf16 v[42:45], v[154:157], v[178:181], v[42:45]
	v_mfma_f32_16x16x32_bf16 v[38:41], v[162:165], v[178:181], v[38:41]
	v_mfma_f32_16x16x32_bf16 v[26:29], v[154:157], v[208:211], v[26:29]
	v_mfma_f32_16x16x32_bf16 v[22:25], v[162:165], v[208:211], v[22:25]
	v_mfma_f32_16x16x32_bf16 v[6:9], v[154:157], v[216:219], v[6:9]
	v_mfma_f32_16x16x32_bf16 v[2:5], v[162:165], v[216:219], v[2:5]
	s_setprio 0
	s_barrier
	s_add_u32 s0, s0, 0x100
	s_addc_u32 s1, s1, 0
	s_add_u32 s40, s40, 0x100
	s_addc_u32 s41, s41, 0
	s_cmp_ge_i32 s42, s81
	s_mov_b32 s22, s42
	s_cbranch_scc0 .LBB0_271
	s_and_b64 vcc, exec, s[16:17]
	s_cbranch_vccnz .LBB0_278
